# speedup vs baseline: 1.0218x; 1.0072x over previous
; #define SBAR() __builtin_amdgcn_sched_barrier(0)
; template <bool ALIBI, bool LAST>
; DEVI void softmax_tile(f32x16& p0, f32x16& p1, const float C, const float nslope2, const float dbase, float& m_reg, float& l_reg, float& alpha,
;                        bf16x8& pa0, bf16x8& pa1, bf16x8& pa2, bf16x8& pa3) {
;   if constexpr (ALIBI) {
; #pragma unroll
;     for (int r = 0; r < 16; ++r) {
;       const float c = (float)((r & 3) + 8 * (r >> 2));
;       p0[r] = fmaf(nslope2, fabsf(dbase - c), p0[r]);
;       p1[r] = fmaf(nslope2, fabsf(dbase - (c + 32.f)), p1[r]);
;     }
;   }
; template <int DQK, bool ALIBI>
; DEVI void attn_pass(const AttnArgs& a, f32x16 (&o)[4], const int tid_) {
;     ...
;       if constexpr (DQK == 128 || DQK == 64 || DQK == 192) {
;         constexpr int NG4 = DQK / 64;
;         bf16x8 ka[4][2], kb[4][2];
; #pragma unroll
;         for (int s = 0; s < 4; ++s) { ka[s][0] = *(const bf16x8*)(Ks + KCB(s)); ka[s][1] = *(const bf16x8*)(Ks + 32 * KPITCH + KCB(s)); }
;         SBAR();
; #pragma unroll
;         for (int g = 0; g < NG4; ++g) {
;           if (g + 1 < NG4) {
; #pragma unroll
;             for (int s = 0; s < 4; ++s) { const int d1 = (g + 1) * 4 + s;
;               if (g & 1) { ka[s][0] = *(const bf16x8*)(Ks + KCB(d1)); ka[s][1] = *(const bf16x8*)(Ks + 32 * KPITCH + KCB(d1)); }
;               else       { kb[s][0] = *(const bf16x8*)(Ks + KCB(d1)); kb[s][1] = *(const bf16x8*)(Ks + 32 * KPITCH + KCB(d1)); } }
;           }
; #pragma unroll
;           for (int s = 0; s < 4; ++s) { const int d0 = g * 4 + s;
;             p0 = __builtin_amdgcn_mfma_f32_32x32x16_bf16((g & 1) ? kb[s][0] : ka[s][0], qr[d0], p0, 0, 0, 0);
;             p1 = __builtin_amdgcn_mfma_f32_32x32x16_bf16((g & 1) ? kb[s][1] : ka[s][1], qr[d0], p1, 0, 0, 0); }
;           SBAR();
.LBB0_186:
	s_and_saveexec_b64 s[62:63], s[4:5]
	s_cbranch_execz .LBB0_192
	v_lshl_add_u32 v0, s50, 13, v190
	v_add_u32_e32 v6, v0, v198
	v_add_u32_e32 v14, v0, v199
	ds_read_b128 v[2:5], v6 offset:32768
	ds_read_b128 v[6:9], v6 offset:36864
	ds_read_b128 v[10:13], v14 offset:32768
	ds_read_b128 v[128:131], v14 offset:36864
	v_add_u32_e32 v14, v0, v200
	v_add_u32_e32 v0, v0, v201
	ds_read_b128 v[206:209], v14 offset:32768
	ds_read_b128 v[210:213], v14 offset:36864
	ds_read_b128 v[214:217], v0 offset:32768
	ds_read_b128 v[218:221], v0 offset:36864
	s_add_i32 s37, s60, s66
	s_cmp_gt_i32 s66, s45
	s_cselect_b32 vcc_lo, s84, s37
	s_cmp_eq_u32 vcc_lo, s84
	s_waitcnt lgkmcnt(0)
	v_mfma_f32_32x32x16_bf16 v[80:95], v[2:5], v[112:115], 0
	v_mfma_f32_32x32x16_bf16 v[96:111], v[6:9], v[112:115], 0
	v_mfma_f32_32x32x16_bf16 v[80:95], v[10:13], v[116:119], v[80:95]
	v_mfma_f32_32x32x16_bf16 v[96:111], v[128:131], v[116:119], v[96:111]
	v_mfma_f32_32x32x16_bf16 v[80:95], v[206:209], v[120:123], v[80:95]
	v_mfma_f32_32x32x16_bf16 v[96:111], v[210:213], v[120:123], v[96:111]
	v_mfma_f32_32x32x16_bf16 v[80:95], v[214:217], v[124:127], v[80:95]
	v_mfma_f32_32x32x16_bf16 v[96:111], v[218:221], v[124:127], v[96:111]
	s_mov_b64 s[66:67], -1
	v_max_f32_e32 v205, v204, v204
	s_cbranch_scc1 .LBB0_194
	s_lshl_b32 s37, vcc_lo, 6
	s_or_b32 s37, s37, 16
	v_cvt_f32_i32_e32 v0, s37
	v_sub_f32_e32 v0, v184, v0
	v_cmp_le_f32_e32 vcc, 0x426c0000, v0
	s_cmp_eq_u64 vcc, exec
	s_cbranch_scc1 .Lmy_C_pos
	v_cmp_ge_f32_e32 vcc, 0, v0
	s_cmp_eq_u64 vcc, exec
	s_cbranch_scc1 .Lmy_C_neg
	v_mov_b32_e32 v131, 0
	v_add_f32_e32 v14, 0xc1200000, v0
	v_add_f32_e32 v3, 0xc2000000, v0
	s_nop 1
	v_fma_f32 v15, v182, |v14|, v86
	v_add_f32_e32 v14, 0xc2280000, v0
	v_fma_f32 v3, v182, |v3|, v96
	v_add_f32_e32 v5, 0xc2040000, v0
	v_fma_f32 v96, v182, |v14|, v102
	v_add_f32_e32 v14, 0xc1300000, v0
	v_fma_f32 v5, v182, |v5|, v97
	v_add_f32_e32 v7, 0xc2080000, v0
	v_fma_f32 v97, v182, |v14|, v87
	v_add_f32_e32 v14, 0xc22c0000, v0
	v_fma_f32 v7, v182, |v7|, v98
	v_fma_f32 v98, v182, |v14|, v103
	v_add_f32_e32 v14, 0xc1800000, v0
	v_add_f32_e32 v9, 0xc20c0000, v0
	v_fma_f32 v88, v182, |v14|, v88
	v_add_f32_e32 v14, 0xc2400000, v0
	v_fma_f32 v9, v182, |v9|, v99
	v_fma_f32 v99, v182, |v14|, v104
	v_add_f32_e32 v14, 0xc1880000, v0
	v_add_f32_e32 v11, 0xc2200000, v0
	v_fma_f32 v89, v182, |v14|, v89
	v_add_f32_e32 v14, 0xc2440000, v0
	v_fma_f32 v11, v182, |v11|, v100
	v_fma_f32 v100, v182, |v14|, v105
	v_add_f32_e32 v14, 0xc1900000, v0
	v_add_f32_e32 v13, 0xc2240000, v0
	v_fma_f32 v90, v182, |v14|, v90
	v_add_f32_e32 v14, 0xc2480000, v0
	v_fma_f32 v13, v182, |v13|, v101
	v_fma_f32 v101, v182, |v14|, v106
	v_add_f32_e32 v14, 0xc1980000, v0
	v_fma_f32 v91, v182, |v14|, v91
	v_add_f32_e32 v14, 0xc24c0000, v0
	v_fma_f32 v102, v182, |v14|, v107
	v_add_f32_e32 v14, 0xc1c00000, v0
	v_fma_f32 v92, v182, |v14|, v92
	v_add_f32_e32 v14, 0xc2600000, v0
	v_fma_f32 v103, v182, |v14|, v108
	v_add_f32_e32 v14, 0xc1c80000, v0
	v_fma_f32 v93, v182, |v14|, v93
	v_add_f32_e32 v14, 0xc2640000, v0
	v_fma_f32 v104, v182, |v14|, v109
	v_add_f32_e32 v14, 0xc1d00000, v0
	v_add_f32_e32 v4, -1.0, v0
	v_fma_f32 v94, v182, |v14|, v94
	v_add_f32_e32 v14, 0xc2680000, v0
	v_fma_f32 v2, v182, |v0|, v80
	v_fma_f32 v4, v182, |v4|, v81
	v_add_f32_e32 v6, -2.0, v0
	v_add_f32_e32 v8, 0xc0400000, v0
	v_add_f32_e32 v10, 0xc1000000, v0
	v_add_f32_e32 v12, 0xc1100000, v0
	v_fma_f32 v105, v182, |v14|, v110
	v_add_f32_e32 v14, 0xc1d80000, v0
	v_add_f32_e32 v0, 0xc26c0000, v0
	v_fma_f32 v6, v182, |v6|, v82
	v_fma_f32 v8, v182, |v8|, v83
	v_fma_f32 v106, v182, |v0|, v111
	v_max_f32_e32 v0, v2, v4
	v_fma_f32 v10, v182, |v10|, v84
	v_fma_f32 v12, v182, |v12|, v85
	v_max3_f32 v0, v0, v6, v8
	v_max3_f32 v0, v0, v10, v12
	v_max3_f32 v0, v0, v15, v97
	v_max3_f32 v0, v0, v88, v89
	v_max3_f32 v0, v0, v90, v91
	v_fma_f32 v95, v182, |v14|, v95
; template <bool ALIBI, bool LAST>
; DEVI void softmax_tile(f32x16& p0, f32x16& p1, const float C, const float nslope2, const float dbase, float& m_reg, float& l_reg, float& alpha,
;                        bf16x8& pa0, bf16x8& pa1, bf16x8& pa2, bf16x8& pa3) {
;     ...
;   float pmax = p0[0];
; #pragma unroll
;   for (int r = 1; r < 16; ++r) pmax = fmaxf(pmax, p0[r]);
;   if constexpr (!LAST) {
; #pragma unroll
;     for (int r = 0; r < 16; ++r) pmax = fmaxf(pmax, p1[r]);
;   }
;   { auto rr = __builtin_amdgcn_permlane32_swap(__float_as_uint(pmax), __float_as_uint(pmax), false, false);
;     pmax = fmaxf(__uint_as_float(rr[0]), __uint_as_float(rr[1])); }
;   const float THRU = 8.f * LOG2E / C;
;   const float CU = C;
;   if (__builtin_expect(__all(pmax - m_reg <= THRU), 1)) { alpha = 1.f; }
;   else { float mn = fmaxf(m_reg, pmax); alpha = __builtin_amdgcn_exp2f((m_reg - mn) * CU); m_reg = mn; }
;   {
;     const float mnC = -m_reg * C;
; #pragma unroll
;     for (int r = 0; r < 16; ++r) { p0[r] = __builtin_amdgcn_exp2f(fmaf(p0[r], C, mnC)); p1[r] = __builtin_amdgcn_exp2f(fmaf(p1[r], C, mnC)); }
;   }
;   float ps = 0.f;
; #pragma unroll
;   for (int r = 0; r < 16; ++r) ps += p0[r];
; #pragma unroll
;   for (int r = 0; r < 16; ++r) ps += p1[r];
;   { auto rr = __builtin_amdgcn_permlane32_swap(__float_as_uint(ps), __float_as_uint(ps), false, false);
;     ps = __uint_as_float(rr[0]) + __uint_as_float(rr[1]); }
;   l_reg = l_reg * alpha + ps;
;     ...
;   PK4(p0, 0, pa0); PK4(p0, 8, pa1); PK4(p1, 0, pa2); PK4(p1, 8, pa3);
.Lmy_C_join:
	v_max3_f32 v0, v0, v92, v93
	v_max3_f32 v0, v0, v94, v95
	v_max3_f32 v0, v0, v3, v5
	v_max3_f32 v0, v0, v7, v9
	v_max3_f32 v0, v0, v11, v13
	v_max3_f32 v0, v0, v96, v98
	v_max3_f32 v0, v0, v99, v100
	v_max3_f32 v0, v0, v101, v102
	v_max3_f32 v0, v0, v103, v104
	v_max3_f32 v0, v0, v105, v106
	v_add_f32_e32 v0, v0, v131
	v_mov_b32_e32 v14, v0
	s_nop 1
	v_permlane32_swap_b32_e32 v0, v14
	v_max_f32_e32 v14, v14, v14
	v_max_f32_e32 v0, v0, v0
	v_max_f32_e32 v0, v0, v14
	v_sub_f32_e32 v14, v0, v204
	v_max_f32_e32 v0, v205, v0
	v_cmp_ge_f32_e32 vcc, s40, v14
	v_sub_f32_e32 v14, v204, v0
	v_mul_f32_e32 v14, 0x3e38aa3b, v14
	v_exp_f32_e32 v107, v14
	s_cmp_eq_u64 vcc, exec
	s_cselect_b64 vcc, -1, 0
	v_cndmask_b32_e32 v14, v0, v204, vcc
	v_cndmask_b32_e64 v0, v107, 1.0, vcc
	v_mul_f32_e32 v107, 0xbe38aa3b, v14
	v_fmac_f32_e32 v107, 0x3e38aa3b, v131
	v_fmamk_f32 v11, v11, 0x3e38aa3b, v107
	v_exp_f32_e32 v108, v11
	v_fmamk_f32 v11, v12, 0x3e38aa3b, v107
	v_fmamk_f32 v12, v13, 0x3e38aa3b, v107
	v_exp_f32_e32 v109, v12
	v_fmamk_f32 v12, v15, 0x3e38aa3b, v107
	v_fmamk_f32 v13, v96, 0x3e38aa3b, v107
	v_fmamk_f32 v15, v98, 0x3e38aa3b, v107
	v_exp_f32_e32 v96, v13
	v_fmamk_f32 v13, v97, 0x3e38aa3b, v107
	v_exp_f32_e32 v97, v15
	v_fmamk_f32 v15, v88, 0x3e38aa3b, v107
	v_exp_f32_e32 v88, v15
	v_fmamk_f32 v15, v99, 0x3e38aa3b, v107
	v_exp_f32_e32 v98, v15
	v_fmamk_f32 v15, v89, 0x3e38aa3b, v107
	v_exp_f32_e32 v89, v15
	v_fmamk_f32 v15, v100, 0x3e38aa3b, v107
	v_exp_f32_e32 v99, v15
	v_fmamk_f32 v15, v90, 0x3e38aa3b, v107
	v_exp_f32_e32 v90, v15
	v_fmamk_f32 v15, v101, 0x3e38aa3b, v107
	v_exp_f32_e32 v100, v15
	v_fmamk_f32 v15, v91, 0x3e38aa3b, v107
	v_exp_f32_e32 v91, v15
	v_fmamk_f32 v15, v102, 0x3e38aa3b, v107
	v_exp_f32_e32 v101, v15
	v_fmamk_f32 v15, v92, 0x3e38aa3b, v107
	v_exp_f32_e32 v92, v15
	v_fmamk_f32 v15, v103, 0x3e38aa3b, v107
	v_fmamk_f32 v2, v2, 0x3e38aa3b, v107
	v_exp_f32_e32 v102, v15
	v_fmamk_f32 v15, v93, 0x3e38aa3b, v107
	v_exp_f32_e32 v2, v2
	v_fmamk_f32 v4, v4, 0x3e38aa3b, v107
	v_exp_f32_e32 v93, v15
	v_fmamk_f32 v15, v104, 0x3e38aa3b, v107
	v_exp_f32_e32 v4, v4
	v_fmamk_f32 v6, v6, 0x3e38aa3b, v107
	v_exp_f32_e32 v103, v15
	v_fmamk_f32 v15, v94, 0x3e38aa3b, v107
	v_exp_f32_e32 v6, v6
	v_fmamk_f32 v8, v8, 0x3e38aa3b, v107
	v_exp_f32_e32 v94, v15
	v_fmamk_f32 v15, v105, 0x3e38aa3b, v107
	v_exp_f32_e32 v8, v8
	v_fmamk_f32 v10, v10, 0x3e38aa3b, v107
	v_exp_f32_e32 v104, v15
	v_fmamk_f32 v15, v95, 0x3e38aa3b, v107
	v_exp_f32_e32 v10, v10
	v_exp_f32_e32 v95, v15
	v_add_f32_e32 v15, 0, v2
	v_exp_f32_e32 v11, v11
	v_add_f32_e32 v15, v4, v15
	v_exp_f32_e32 v12, v12
	v_add_f32_e32 v15, v6, v15
	v_exp_f32_e32 v13, v13
	v_add_f32_e32 v15, v8, v15
	v_add_f32_e32 v15, v10, v15
	v_add_f32_e32 v15, v11, v15
	v_add_f32_e32 v15, v12, v15
	v_add_f32_e32 v15, v13, v15
	v_add_f32_e32 v15, v88, v15
	v_add_f32_e32 v15, v89, v15
	v_add_f32_e32 v15, v90, v15
	v_fmamk_f32 v3, v3, 0x3e38aa3b, v107
	v_add_f32_e32 v15, v91, v15
	v_exp_f32_e32 v3, v3
	v_fmamk_f32 v5, v5, 0x3e38aa3b, v107
	v_add_f32_e32 v15, v92, v15
	v_exp_f32_e32 v5, v5
	v_fmamk_f32 v7, v7, 0x3e38aa3b, v107
	v_add_f32_e32 v15, v93, v15
	v_exp_f32_e32 v7, v7
	v_fmamk_f32 v9, v9, 0x3e38aa3b, v107
	v_add_f32_e32 v15, v94, v15
	v_exp_f32_e32 v9, v9
	v_add_f32_e32 v15, v95, v15
	v_add_f32_e32 v15, v3, v15
	v_add_f32_e32 v15, v5, v15
	v_add_f32_e32 v15, v7, v15
	v_add_f32_e32 v15, v9, v15
	v_add_f32_e32 v15, v108, v15
	v_add_f32_e32 v15, v109, v15
	v_add_f32_e32 v15, v96, v15
	v_add_f32_e32 v15, v97, v15
	v_add_f32_e32 v15, v98, v15
	v_add_f32_e32 v15, v99, v15
	v_fmac_f32_e32 v107, 0x3e38aa3b, v106
	v_add_f32_e32 v15, v100, v15
	v_exp_f32_e32 v105, v107
	v_add_f32_e32 v15, v101, v15
	v_add_f32_e32 v15, v102, v15
	v_add_f32_e32 v15, v103, v15
	v_add_f32_e32 v15, v104, v15
	v_add_f32_e32 v15, v105, v15
	v_mov_b32_e32 v106, v15
	s_nop 1
	v_permlane32_swap_b32_e32 v15, v106
	v_add_f32_e32 v15, v15, v106
	v_cvt_pk_bf16_f32 v128, v2, v4
	v_cvt_pk_bf16_f32 v129, v6, v8
	v_cvt_pk_bf16_f32 v130, v10, v11
	v_cvt_pk_bf16_f32 v131, v12, v13
	v_cvt_pk_bf16_f32 v10, v88, v89
	v_cvt_pk_bf16_f32 v11, v90, v91
	v_cvt_pk_bf16_f32 v12, v92, v93
	v_cvt_pk_bf16_f32 v13, v94, v95
	v_cvt_pk_bf16_f32 v6, v3, v5
	v_cvt_pk_bf16_f32 v7, v7, v9
	v_cvt_pk_bf16_f32 v8, v108, v109
	v_cvt_pk_bf16_f32 v9, v96, v97
	v_cvt_pk_bf16_f32 v2, v98, v99
	v_cvt_pk_bf16_f32 v3, v100, v101
	v_cvt_pk_bf16_f32 v4, v102, v103
	v_cvt_pk_bf16_f32 v5, v104, v105
	v_fmac_f32_e32 v15, v203, v0
	v_permlane32_swap_b32_e32 v128, v130
	v_permlane32_swap_b32_e32 v129, v131
	v_permlane32_swap_b32_e32 v10, v12
	v_permlane32_swap_b32_e32 v11, v13
	v_permlane32_swap_b32_e32 v6, v8
	v_permlane32_swap_b32_e32 v7, v9
	v_permlane32_swap_b32_e32 v2, v4
	v_permlane32_swap_b32_e32 v3, v5
	s_cbranch_execz .LBB0_195

; template <bool ALIBI, bool LAST>
; DEVI void softmax_tile(f32x16& p0, f32x16& p1, const float C, const float nslope2, const float dbase, float& m_reg, float& l_reg, float& alpha,
;                        bf16x8& pa0, bf16x8& pa1, bf16x8& pa2, bf16x8& pa3) {
;   if constexpr (ALIBI) {
; #pragma unroll
;     for (int r = 0; r < 16; ++r) {
;       const float c = (float)((r & 3) + 8 * (r >> 2));
;       p0[r] = fmaf(nslope2, fabsf(dbase - c), p0[r]);
;       p1[r] = fmaf(nslope2, fabsf(dbase - (c + 32.f)), p1[r]);
;     }
;   }
;   if constexpr (LAST) {
; #pragma unroll
;     for (int r = 8; r < 16; ++r) p0[r] = -1e30f;
; #pragma unroll
;     for (int r = 0; r < 16; ++r) p1[r] = -1e30f;
;   }
;   float pmax = p0[0];
; #pragma unroll
;   for (int r = 1; r < 16; ++r) pmax = fmaxf(pmax, p0[r]);
.Lmy_C_pos:
	s_nop 1
	v_mul_f32_e32 v131, v182, v0
	v_fmamk_f32 v15, v182, 0xc1200000, v86
	v_fmamk_f32 v3, v182, 0xc2000000, v96
	v_fmamk_f32 v96, v182, 0xc2280000, v102
	v_fmamk_f32 v5, v182, 0xc2040000, v97
	v_fmamk_f32 v97, v182, 0xc1300000, v87
	v_fmamk_f32 v7, v182, 0xc2080000, v98
	v_fmamk_f32 v98, v182, 0xc22c0000, v103
	v_fmamk_f32 v88, v182, 0xc1800000, v88
	v_fmamk_f32 v9, v182, 0xc20c0000, v99
	v_fmamk_f32 v99, v182, 0xc2400000, v104
	v_fmamk_f32 v89, v182, 0xc1880000, v89
	v_fmamk_f32 v11, v182, 0xc2200000, v100
	v_fmamk_f32 v100, v182, 0xc2440000, v105
	v_fmamk_f32 v90, v182, 0xc1900000, v90
	v_fmamk_f32 v13, v182, 0xc2240000, v101
	v_fmamk_f32 v101, v182, 0xc2480000, v106
	v_fmamk_f32 v91, v182, 0xc1980000, v91
	v_fmamk_f32 v102, v182, 0xc24c0000, v107
	v_fmamk_f32 v92, v182, 0xc1c00000, v92
	v_fmamk_f32 v103, v182, 0xc2600000, v108
	v_fmamk_f32 v93, v182, 0xc1c80000, v93
	v_fmamk_f32 v104, v182, 0xc2640000, v109
	v_fmamk_f32 v94, v182, 0xc1d00000, v94
	v_fmamk_f32 v2, v182, 0x00000000, v80
	v_fmamk_f32 v4, v182, 0xbf800000, v81
	v_fmamk_f32 v105, v182, 0xc2680000, v110
	v_fmamk_f32 v6, v182, 0xc0000000, v82
	v_fmamk_f32 v8, v182, 0xc0400000, v83
	v_fmamk_f32 v106, v182, 0xc26c0000, v111
	v_max_f32_e32 v0, v2, v4
	v_fmamk_f32 v10, v182, 0xc1000000, v84
	v_fmamk_f32 v12, v182, 0xc1100000, v85
	v_max3_f32 v0, v0, v6, v8
	v_max3_f32 v0, v0, v10, v12
	v_max3_f32 v0, v0, v15, v97
	v_max3_f32 v0, v0, v88, v89
	v_max3_f32 v0, v0, v90, v91
	v_fmamk_f32 v95, v182, 0xc1d80000, v95
	s_branch .Lmy_C_join
.Lmy_C_neg:
	s_nop 1
	v_mul_f32_e64 v131, v182, -v0
	v_fmamk_f32 v15, v182, 0x41200000, v86
	v_fmamk_f32 v3, v182, 0x42000000, v96
	v_fmamk_f32 v96, v182, 0x42280000, v102
	v_fmamk_f32 v5, v182, 0x42040000, v97
	v_fmamk_f32 v97, v182, 0x41300000, v87
	v_fmamk_f32 v7, v182, 0x42080000, v98
	v_fmamk_f32 v98, v182, 0x422c0000, v103
	v_fmamk_f32 v88, v182, 0x41800000, v88
	v_fmamk_f32 v9, v182, 0x420c0000, v99
	v_fmamk_f32 v99, v182, 0x42400000, v104
	v_fmamk_f32 v89, v182, 0x41880000, v89
	v_fmamk_f32 v11, v182, 0x42200000, v100
	v_fmamk_f32 v100, v182, 0x42440000, v105
	v_fmamk_f32 v90, v182, 0x41900000, v90
	v_fmamk_f32 v13, v182, 0x42240000, v101
	v_fmamk_f32 v101, v182, 0x42480000, v106
	v_fmamk_f32 v91, v182, 0x41980000, v91
	v_fmamk_f32 v102, v182, 0x424c0000, v107
	v_fmamk_f32 v92, v182, 0x41c00000, v92
	v_fmamk_f32 v103, v182, 0x42600000, v108
	v_fmamk_f32 v93, v182, 0x41c80000, v93
	v_fmamk_f32 v104, v182, 0x42640000, v109
	v_fmamk_f32 v94, v182, 0x41d00000, v94
	v_fmamk_f32 v2, v182, 0x00000000, v80
	v_fmamk_f32 v4, v182, 0x3f800000, v81
	v_fmamk_f32 v105, v182, 0x42680000, v110
	v_fmamk_f32 v6, v182, 0x40000000, v82
	v_fmamk_f32 v8, v182, 0x40400000, v83
	v_fmamk_f32 v106, v182, 0x426c0000, v111
	v_max_f32_e32 v0, v2, v4
	v_fmamk_f32 v10, v182, 0x41000000, v84
	v_fmamk_f32 v12, v182, 0x41100000, v85
	v_max3_f32 v0, v0, v6, v8
	v_max3_f32 v0, v0, v10, v12
	v_max3_f32 v0, v0, v15, v97
	v_max3_f32 v0, v0, v88, v89
	v_max3_f32 v0, v0, v90, v91
	v_fmamk_f32 v95, v182, 0x41d80000, v95
	s_branch .Lmy_C_join

; #define SBAR() __builtin_amdgcn_sched_barrier(0)
; #define RD8(KS, P) const s16x4 P##l0 = tr_read<v_rd_off(0, KS, 0)>(vb), P##h0 = tr_read<v_rd_off(0, KS, 1)>(vb), P##l1 = tr_read<v_rd_off(1, KS, 0)>(vb), P##h1 = tr_read<v_rd_off(1, KS, 1)>(vb), \
;                                P##l2 = tr_read<v_rd_off(2, KS, 0)>(vb), P##h2 = tr_read<v_rd_off(2, KS, 1)>(vb), P##l3 = tr_read<v_rd_off(3, KS, 0)>(vb), P##h3 = tr_read<v_rd_off(3, KS, 1)>(vb)
; DEVI void pv_all(f32x16 (&o)[4], int vb, bf16x8 pa0, bf16x8 pa1, bf16x8 pa2, bf16x8 pa3) {
;     ...
;   RD8(0, a); RD8(1, b);
;   asm volatile("s_waitcnt lgkmcnt(8)" ::: "memory"); SBAR(); MM4(a, pa0); SBAR();
;   RD8(2, c);
;   asm volatile("s_waitcnt lgkmcnt(8)" ::: "memory"); SBAR(); MM4(b, pa1); SBAR();
;   RD8(3, d);
;   asm volatile("s_waitcnt lgkmcnt(8)" ::: "memory"); SBAR(); MM4(c, pa2); SBAR();
;   asm volatile("s_waitcnt lgkmcnt(0)" ::: "memory"); SBAR(); MM4(d, pa3);
; template <bool ALIBI, bool LAST>
; DEVI void softmax_tile(f32x16& p0, f32x16& p1, const float C, const float nslope2, const float dbase, float& m_reg, float& l_reg, float& alpha,
;                        bf16x8& pa0, bf16x8& pa1, bf16x8& pa2, bf16x8& pa3) {
;     ...
;   {
;     const float mnC = -m_reg * C;
; #pragma unroll
;     for (int r = 0; r < 16; ++r) { p0[r] = __builtin_amdgcn_exp2f(fmaf(p0[r], C, mnC)); p1[r] = __builtin_amdgcn_exp2f(fmaf(p1[r], C, mnC)); }
;   }
;   float ps = 0.f;
; #pragma unroll
;   for (int r = 0; r < 16; ++r) ps += p0[r];
; #pragma unroll
;   for (int r = 0; r < 16; ++r) ps += p1[r];
;   { auto rr = __builtin_amdgcn_permlane32_swap(__float_as_uint(ps), __float_as_uint(ps), false, false);
;     ps = __uint_as_float(rr[0]) + __uint_as_float(rr[1]); }
;   l_reg = l_reg * alpha + ps;
;     ...
;   PK4(p0, 0, pa0); PK4(p0, 8, pa1); PK4(p1, 0, pa2); PK4(p1, 8, pa3);
.Lmy_B_cont:
	v_mul_f32_e32 v238, 0xbdd53b94, v199
	ds_read_b64_tr_b16 v[220:221], v236 offset:0x1000
	ds_read_b64_tr_b16 v[222:223], v236 offset:0x1800
	ds_read_b64_tr_b16 v[224:225], v236 offset:0x1200
	ds_read_b64_tr_b16 v[226:227], v236 offset:0x1a00
	ds_read_b64_tr_b16 v[228:229], v236 offset:0x1400
	ds_read_b64_tr_b16 v[230:231], v236 offset:0x1c00
	ds_read_b64_tr_b16 v[232:233], v236 offset:0x1600
	ds_read_b64_tr_b16 v[234:235], v236 offset:0x1e00
	v_fmamk_f32 v82, v82, 0x3dd53b94, v238
	v_fmamk_f32 v83, v83, 0x3dd53b94, v238
	v_exp_f32_e32 v82, v82
	v_fmamk_f32 v84, v84, 0x3dd53b94, v238
	v_exp_f32_e32 v83, v83
	v_fmamk_f32 v85, v85, 0x3dd53b94, v238
	v_exp_f32_e32 v84, v84
	v_fmamk_f32 v86, v86, 0x3dd53b94, v238
	v_exp_f32_e32 v85, v85
	v_add_f32_e32 v237, v82, v83
	v_fmamk_f32 v87, v87, 0x3dd53b94, v238
	v_exp_f32_e32 v86, v86
	v_add_f32_e32 v237, v84, v237
	v_fmamk_f32 v88, v88, 0x3dd53b94, v238
	v_exp_f32_e32 v87, v87
	v_add_f32_e32 v237, v85, v237
	v_fmamk_f32 v89, v89, 0x3dd53b94, v238
	v_exp_f32_e32 v88, v88
	v_add_f32_e32 v237, v86, v237
	v_fmamk_f32 v90, v90, 0x3dd53b94, v238
	v_exp_f32_e32 v89, v89
	v_add_f32_e32 v237, v87, v237
	v_fmamk_f32 v91, v91, 0x3dd53b94, v238
	v_exp_f32_e32 v90, v90
	v_add_f32_e32 v237, v88, v237
	v_fmamk_f32 v92, v92, 0x3dd53b94, v238
	v_exp_f32_e32 v91, v91
	v_add_f32_e32 v237, v89, v237
	v_fmamk_f32 v93, v93, 0x3dd53b94, v238
	v_exp_f32_e32 v92, v92
	v_add_f32_e32 v237, v90, v237
	v_cvt_pk_bf16_f32 v89, v88, v89
	v_fmamk_f32 v94, v94, 0x3dd53b94, v238
	v_exp_f32_e32 v93, v93
	v_add_f32_e32 v237, v91, v237
	v_cvt_pk_bf16_f32 v88, v86, v87
	v_fmamk_f32 v95, v95, 0x3dd53b94, v238
	v_exp_f32_e32 v94, v94
	v_add_f32_e32 v237, v92, v237
	v_cvt_pk_bf16_f32 v87, v84, v85
	v_fmamk_f32 v96, v96, 0x3dd53b94, v238
	v_exp_f32_e32 v95, v95
	v_add_f32_e32 v237, v93, v237
	v_cvt_pk_bf16_f32 v86, v82, v83
	v_fmamk_f32 v97, v97, 0x3dd53b94, v238
	v_exp_f32_e32 v96, v96
	v_add_f32_e32 v237, v94, v237
	v_fmamk_f32 v66, v66, 0x3dd53b94, v238
	v_exp_f32_e32 v97, v97
	v_add_f32_e32 v237, v95, v237
	v_permlane32_swap_b32_e32 v86, v88
	v_fmamk_f32 v67, v67, 0x3dd53b94, v238
	v_exp_f32_e32 v66, v66
	v_add_f32_e32 v237, v96, v237
	v_permlane32_swap_b32_e32 v87, v89
	v_fmamk_f32 v68, v68, 0x3dd53b94, v238
	v_exp_f32_e32 v67, v67
	v_add_f32_e32 v237, v97, v237
	s_waitcnt lgkmcnt(8)
	v_mfma_f32_32x32x16_bf16 v[2:17], v[204:207], v[86:89], v[2:17]
	v_fmamk_f32 v69, v69, 0x3dd53b94, v238
	v_exp_f32_e32 v68, v68
	v_add_f32_e32 v237, v66, v237
	v_cvt_pk_bf16_f32 v97, v96, v97
	v_fmamk_f32 v70, v70, 0x3dd53b94, v238
	v_exp_f32_e32 v69, v69
	v_add_f32_e32 v237, v67, v237
	v_cvt_pk_bf16_f32 v96, v94, v95
	v_mfma_f32_32x32x16_bf16 v[18:33], v[208:211], v[86:89], v[18:33]
	v_fmamk_f32 v71, v71, 0x3dd53b94, v238
	v_exp_f32_e32 v70, v70
	v_add_f32_e32 v237, v68, v237
	v_cvt_pk_bf16_f32 v95, v92, v93
	v_fmamk_f32 v72, v72, 0x3dd53b94, v238
	v_exp_f32_e32 v71, v71
	v_add_f32_e32 v237, v69, v237
	v_cvt_pk_bf16_f32 v94, v90, v91
	v_mfma_f32_32x32x16_bf16 v[34:49], v[212:215], v[86:89], v[34:49]
	v_fmamk_f32 v73, v73, 0x3dd53b94, v238
	v_exp_f32_e32 v72, v72
	v_add_f32_e32 v237, v70, v237
	v_fmamk_f32 v74, v74, 0x3dd53b94, v238
	v_exp_f32_e32 v73, v73
	v_add_f32_e32 v237, v71, v237
	v_permlane32_swap_b32_e32 v94, v96
	v_mfma_f32_32x32x16_bf16 v[50:65], v[216:219], v[86:89], v[50:65]
	ds_read_b64_tr_b16 v[204:205], v236 offset:0x2000
	ds_read_b64_tr_b16 v[206:207], v236 offset:0x2800
	ds_read_b64_tr_b16 v[208:209], v236 offset:0x2200
	ds_read_b64_tr_b16 v[210:211], v236 offset:0x2a00
	ds_read_b64_tr_b16 v[212:213], v236 offset:0x2400
	ds_read_b64_tr_b16 v[214:215], v236 offset:0x2c00
	ds_read_b64_tr_b16 v[216:217], v236 offset:0x2600
	ds_read_b64_tr_b16 v[218:219], v236 offset:0x2e00
	v_fmamk_f32 v75, v75, 0x3dd53b94, v238
	v_exp_f32_e32 v74, v74
	v_add_f32_e32 v237, v72, v237
	v_permlane32_swap_b32_e32 v95, v97
	v_fmamk_f32 v76, v76, 0x3dd53b94, v238
	v_exp_f32_e32 v75, v75
	v_add_f32_e32 v237, v73, v237
	s_waitcnt lgkmcnt(8)
	v_mfma_f32_32x32x16_bf16 v[2:17], v[220:223], v[94:97], v[2:17]
	v_fmamk_f32 v77, v77, 0x3dd53b94, v238
	v_exp_f32_e32 v76, v76
	v_add_f32_e32 v237, v74, v237
	v_cvt_pk_bf16_f32 v73, v72, v73
	v_fmamk_f32 v78, v78, 0x3dd53b94, v238
	v_exp_f32_e32 v77, v77
	v_add_f32_e32 v237, v75, v237
	v_cvt_pk_bf16_f32 v72, v70, v71
	v_mfma_f32_32x32x16_bf16 v[18:33], v[224:227], v[94:97], v[18:33]
	v_fmamk_f32 v79, v79, 0x3dd53b94, v238
	v_exp_f32_e32 v78, v78
	v_add_f32_e32 v237, v76, v237
	v_cvt_pk_bf16_f32 v71, v68, v69
	v_fmamk_f32 v80, v80, 0x3dd53b94, v238
	v_exp_f32_e32 v79, v79
	v_add_f32_e32 v237, v77, v237
	v_cvt_pk_bf16_f32 v70, v66, v67
	v_mfma_f32_32x32x16_bf16 v[34:49], v[228:231], v[94:97], v[34:49]
	v_fmamk_f32 v81, v81, 0x3dd53b94, v238
	v_exp_f32_e32 v80, v80
	v_add_f32_e32 v237, v78, v237
	v_exp_f32_e32 v81, v81
	v_add_f32_e32 v237, v79, v237
	v_mfma_f32_32x32x16_bf16 v[50:65], v[232:235], v[94:97], v[50:65]
	ds_read_b64_tr_b16 v[220:221], v236 offset:0x3000
	ds_read_b64_tr_b16 v[222:223], v236 offset:0x3800
	ds_read_b64_tr_b16 v[224:225], v236 offset:0x3200
	ds_read_b64_tr_b16 v[226:227], v236 offset:0x3a00
	ds_read_b64_tr_b16 v[228:229], v236 offset:0x3400
	ds_read_b64_tr_b16 v[230:231], v236 offset:0x3c00
	ds_read_b64_tr_b16 v[232:233], v236 offset:0x3600
	ds_read_b64_tr_b16 v[234:235], v236 offset:0x3e00
	v_permlane32_swap_b32_e32 v70, v72
	v_add_f32_e32 v237, v80, v237
	v_permlane32_swap_b32_e32 v71, v73
	v_add_f32_e32 v237, v81, v237
	v_cvt_pk_bf16_f32 v81, v80, v81
	s_waitcnt lgkmcnt(8)
	v_mfma_f32_32x32x16_bf16 v[2:17], v[204:207], v[70:73], v[2:17]
	v_cvt_pk_bf16_f32 v80, v78, v79
	v_cvt_pk_bf16_f32 v79, v76, v77
	v_mfma_f32_32x32x16_bf16 v[18:33], v[208:211], v[70:73], v[18:33]
	v_cvt_pk_bf16_f32 v78, v74, v75
	v_mov_b32_e32 v169, v237
	v_mfma_f32_32x32x16_bf16 v[34:49], v[212:215], v[70:73], v[34:49]
	v_permlane32_swap_b32_e32 v78, v80
	v_permlane32_swap_b32_e32 v79, v81
	v_permlane32_swap_b32_e32 v237, v169
	v_mfma_f32_32x32x16_bf16 v[50:65], v[216:219], v[70:73], v[50:65]
	v_add_f32_e32 v169, v237, v169
	v_fmac_f32_e32 v169, v149, v168
	v_mov_b32_e32 v149, v169
	s_waitcnt lgkmcnt(0)
	v_mfma_f32_32x32x16_bf16 v[2:17], v[220:223], v[78:81], v[2:17]
	v_mfma_f32_32x32x16_bf16 v[18:33], v[224:227], v[78:81], v[18:33]
	v_mfma_f32_32x32x16_bf16 v[34:49], v[228:231], v[78:81], v[34:49]
	v_mfma_f32_32x32x16_bf16 v[50:65], v[232:235], v[78:81], v[50:65]
	s_branch .LBB0_210

; #define SBAR() __builtin_amdgcn_sched_barrier(0)
; #define RD8(KS, P) const s16x4 P##l0 = tr_read<v_rd_off(0, KS, 0)>(vb), P##h0 = tr_read<v_rd_off(0, KS, 1)>(vb), P##l1 = tr_read<v_rd_off(1, KS, 0)>(vb), P##h1 = tr_read<v_rd_off(1, KS, 1)>(vb), \
;                                P##l2 = tr_read<v_rd_off(2, KS, 0)>(vb), P##h2 = tr_read<v_rd_off(2, KS, 1)>(vb), P##l3 = tr_read<v_rd_off(3, KS, 0)>(vb), P##h3 = tr_read<v_rd_off(3, KS, 1)>(vb)
; DEVI void pv_all(f32x16 (&o)[4], int vb, bf16x8 pa0, bf16x8 pa1, bf16x8 pa2, bf16x8 pa3) {
;     ...
;   RD8(0, a); RD8(1, b);
;   asm volatile("s_waitcnt lgkmcnt(8)" ::: "memory"); SBAR(); MM4(a, pa0); SBAR();
;   RD8(2, c);
;   asm volatile("s_waitcnt lgkmcnt(8)" ::: "memory"); SBAR(); MM4(b, pa1); SBAR();
;   RD8(3, d);
;   asm volatile("s_waitcnt lgkmcnt(8)" ::: "memory"); SBAR(); MM4(c, pa2); SBAR();
;   asm volatile("s_waitcnt lgkmcnt(0)" ::: "memory"); SBAR(); MM4(d, pa3);
; template <bool ALIBI, bool LAST>
; DEVI void softmax_tile(f32x16& p0, f32x16& p1, const float C, const float nslope2, const float dbase, float& m_reg, float& l_reg, float& alpha,
;                        bf16x8& pa0, bf16x8& pa1, bf16x8& pa2, bf16x8& pa3) {
;     ...
;   {
;     const float mnC = -m_reg * C;
; #pragma unroll
;     for (int r = 0; r < 16; ++r) { p0[r] = __builtin_amdgcn_exp2f(fmaf(p0[r], C, mnC)); p1[r] = __builtin_amdgcn_exp2f(fmaf(p1[r], C, mnC)); }
;   }
;   float ps = 0.f;
; #pragma unroll
;   for (int r = 0; r < 16; ++r) ps += p0[r];
; #pragma unroll
;   for (int r = 0; r < 16; ++r) ps += p1[r];
;   { auto rr = __builtin_amdgcn_permlane32_swap(__float_as_uint(ps), __float_as_uint(ps), false, false);
;     ps = __uint_as_float(rr[0]) + __uint_as_float(rr[1]); }
;   l_reg = l_reg * alpha + ps;
;     ...
;   PK4(p0, 0, pa0); PK4(p0, 8, pa1); PK4(p1, 0, pa2); PK4(p1, 8, pa3);
.Lmy_A_cont:
	v_mul_f32_e32 v208, 0xbe0293ee, v151
	ds_read_b64_tr_b16 v[160:161], v211 offset:0x1000
	ds_read_b64_tr_b16 v[162:163], v211 offset:0x1800
	ds_read_b64_tr_b16 v[164:165], v211 offset:0x1200
	ds_read_b64_tr_b16 v[166:167], v211 offset:0x1a00
	ds_read_b64_tr_b16 v[184:185], v211 offset:0x1400
	ds_read_b64_tr_b16 v[186:187], v211 offset:0x1c00
	ds_read_b64_tr_b16 v[188:189], v211 offset:0x1600
	ds_read_b64_tr_b16 v[190:191], v211 offset:0x1e00
	v_fmamk_f32 v82, v82, 0x3e0293ee, v208
	v_fmamk_f32 v83, v83, 0x3e0293ee, v208
	v_exp_f32_e32 v82, v82
	v_fmamk_f32 v84, v84, 0x3e0293ee, v208
	v_exp_f32_e32 v83, v83
	v_fmamk_f32 v85, v85, 0x3e0293ee, v208
	v_exp_f32_e32 v84, v84
	v_fmamk_f32 v86, v86, 0x3e0293ee, v208
	v_exp_f32_e32 v85, v85
	v_add_f32_e32 v210, v82, v83
	v_fmamk_f32 v87, v87, 0x3e0293ee, v208
	v_exp_f32_e32 v86, v86
	v_add_f32_e32 v210, v84, v210
	v_fmamk_f32 v88, v88, 0x3e0293ee, v208
	v_exp_f32_e32 v87, v87
	v_add_f32_e32 v210, v85, v210
	v_fmamk_f32 v89, v89, 0x3e0293ee, v208
	v_exp_f32_e32 v88, v88
	v_add_f32_e32 v210, v86, v210
	v_fmamk_f32 v90, v90, 0x3e0293ee, v208
	v_exp_f32_e32 v89, v89
	v_add_f32_e32 v210, v87, v210
	v_fmamk_f32 v91, v91, 0x3e0293ee, v208
	v_exp_f32_e32 v90, v90
	v_add_f32_e32 v210, v88, v210
	v_fmamk_f32 v92, v92, 0x3e0293ee, v208
	v_exp_f32_e32 v91, v91
	v_add_f32_e32 v210, v89, v210
	v_fmamk_f32 v93, v93, 0x3e0293ee, v208
	v_exp_f32_e32 v92, v92
	v_add_f32_e32 v210, v90, v210
	v_cvt_pk_bf16_f32 v89, v88, v89
	v_fmamk_f32 v94, v94, 0x3e0293ee, v208
	v_exp_f32_e32 v93, v93
	v_add_f32_e32 v210, v91, v210
	v_cvt_pk_bf16_f32 v88, v86, v87
	v_fmamk_f32 v95, v95, 0x3e0293ee, v208
	v_exp_f32_e32 v94, v94
	v_add_f32_e32 v210, v92, v210
	v_cvt_pk_bf16_f32 v87, v84, v85
	v_fmamk_f32 v96, v96, 0x3e0293ee, v208
	v_exp_f32_e32 v95, v95
	v_add_f32_e32 v210, v93, v210
	v_cvt_pk_bf16_f32 v86, v82, v83
	v_fmamk_f32 v97, v97, 0x3e0293ee, v208
	v_exp_f32_e32 v96, v96
	v_add_f32_e32 v210, v94, v210
	v_fmamk_f32 v66, v66, 0x3e0293ee, v208
	v_exp_f32_e32 v97, v97
	v_add_f32_e32 v210, v95, v210
	v_permlane32_swap_b32_e32 v86, v88
	v_fmamk_f32 v67, v67, 0x3e0293ee, v208
	v_exp_f32_e32 v66, v66
	v_add_f32_e32 v210, v96, v210
	v_permlane32_swap_b32_e32 v87, v89
	v_fmamk_f32 v68, v68, 0x3e0293ee, v208
	v_exp_f32_e32 v67, v67
	v_add_f32_e32 v210, v97, v210
	s_waitcnt lgkmcnt(8)
	v_mfma_f32_32x32x16_bf16 v[2:17], v[192:195], v[86:89], v[2:17]
	v_fmamk_f32 v69, v69, 0x3e0293ee, v208
	v_exp_f32_e32 v68, v68
	v_add_f32_e32 v210, v66, v210
	v_cvt_pk_bf16_f32 v97, v96, v97
	v_fmamk_f32 v70, v70, 0x3e0293ee, v208
	v_exp_f32_e32 v69, v69
	v_add_f32_e32 v210, v67, v210
	v_cvt_pk_bf16_f32 v96, v94, v95
	v_mfma_f32_32x32x16_bf16 v[18:33], v[196:199], v[86:89], v[18:33]
	v_fmamk_f32 v71, v71, 0x3e0293ee, v208
	v_exp_f32_e32 v70, v70
	v_add_f32_e32 v210, v68, v210
	v_cvt_pk_bf16_f32 v95, v92, v93
	v_fmamk_f32 v72, v72, 0x3e0293ee, v208
	v_exp_f32_e32 v71, v71
	v_add_f32_e32 v210, v69, v210
	v_cvt_pk_bf16_f32 v94, v90, v91
	v_mfma_f32_32x32x16_bf16 v[34:49], v[200:203], v[86:89], v[34:49]
	v_fmamk_f32 v73, v73, 0x3e0293ee, v208
	v_exp_f32_e32 v72, v72
	v_add_f32_e32 v210, v70, v210
	v_fmamk_f32 v74, v74, 0x3e0293ee, v208
	v_exp_f32_e32 v73, v73
	v_add_f32_e32 v210, v71, v210
	v_permlane32_swap_b32_e32 v94, v96
	v_mfma_f32_32x32x16_bf16 v[50:65], v[204:207], v[86:89], v[50:65]
	ds_read_b64_tr_b16 v[192:193], v211 offset:0x2000
	ds_read_b64_tr_b16 v[194:195], v211 offset:0x2800
	ds_read_b64_tr_b16 v[196:197], v211 offset:0x2200
	ds_read_b64_tr_b16 v[198:199], v211 offset:0x2a00
	ds_read_b64_tr_b16 v[200:201], v211 offset:0x2400
	ds_read_b64_tr_b16 v[202:203], v211 offset:0x2c00
	ds_read_b64_tr_b16 v[204:205], v211 offset:0x2600
	ds_read_b64_tr_b16 v[206:207], v211 offset:0x2e00
	v_fmamk_f32 v75, v75, 0x3e0293ee, v208
	v_exp_f32_e32 v74, v74
	v_add_f32_e32 v210, v72, v210
	v_permlane32_swap_b32_e32 v95, v97
	v_fmamk_f32 v76, v76, 0x3e0293ee, v208
	v_exp_f32_e32 v75, v75
	v_add_f32_e32 v210, v73, v210
	s_waitcnt lgkmcnt(8)
	v_mfma_f32_32x32x16_bf16 v[2:17], v[160:163], v[94:97], v[2:17]
	v_fmamk_f32 v77, v77, 0x3e0293ee, v208
	v_exp_f32_e32 v76, v76
	v_add_f32_e32 v210, v74, v210
	v_cvt_pk_bf16_f32 v73, v72, v73
	v_fmamk_f32 v78, v78, 0x3e0293ee, v208
	v_exp_f32_e32 v77, v77
	v_add_f32_e32 v210, v75, v210
	v_cvt_pk_bf16_f32 v72, v70, v71
	v_mfma_f32_32x32x16_bf16 v[18:33], v[164:167], v[94:97], v[18:33]
	v_fmamk_f32 v79, v79, 0x3e0293ee, v208
	v_exp_f32_e32 v78, v78
	v_add_f32_e32 v210, v76, v210
	v_cvt_pk_bf16_f32 v71, v68, v69
	v_fmamk_f32 v80, v80, 0x3e0293ee, v208
	v_exp_f32_e32 v79, v79
	v_add_f32_e32 v210, v77, v210
	v_cvt_pk_bf16_f32 v70, v66, v67
	v_mfma_f32_32x32x16_bf16 v[34:49], v[184:187], v[94:97], v[34:49]
	v_fmamk_f32 v81, v81, 0x3e0293ee, v208
	v_exp_f32_e32 v80, v80
	v_add_f32_e32 v210, v78, v210
	v_exp_f32_e32 v81, v81
	v_add_f32_e32 v210, v79, v210
	v_mfma_f32_32x32x16_bf16 v[50:65], v[188:191], v[94:97], v[50:65]
	ds_read_b64_tr_b16 v[160:161], v211 offset:0x3000
	ds_read_b64_tr_b16 v[162:163], v211 offset:0x3800
	ds_read_b64_tr_b16 v[164:165], v211 offset:0x3200
	ds_read_b64_tr_b16 v[166:167], v211 offset:0x3a00
	ds_read_b64_tr_b16 v[184:185], v211 offset:0x3400
	ds_read_b64_tr_b16 v[186:187], v211 offset:0x3c00
	ds_read_b64_tr_b16 v[188:189], v211 offset:0x3600
	ds_read_b64_tr_b16 v[190:191], v211 offset:0x3e00
	v_permlane32_swap_b32_e32 v70, v72
	v_add_f32_e32 v210, v80, v210
	v_permlane32_swap_b32_e32 v71, v73
	v_add_f32_e32 v210, v81, v210
	v_cvt_pk_bf16_f32 v81, v80, v81
	s_waitcnt lgkmcnt(8)
	v_mfma_f32_32x32x16_bf16 v[2:17], v[192:195], v[70:73], v[2:17]
	v_cvt_pk_bf16_f32 v80, v78, v79
	v_cvt_pk_bf16_f32 v79, v76, v77
	v_mfma_f32_32x32x16_bf16 v[18:33], v[196:199], v[70:73], v[18:33]
	v_cvt_pk_bf16_f32 v78, v74, v75
	v_mov_b32_e32 v168, v210
	v_mfma_f32_32x32x16_bf16 v[34:49], v[200:203], v[70:73], v[34:49]
	v_permlane32_swap_b32_e32 v78, v80
	v_permlane32_swap_b32_e32 v79, v81
	v_permlane32_swap_b32_e32 v210, v168
	v_mfma_f32_32x32x16_bf16 v[50:65], v[204:207], v[70:73], v[50:65]
	v_add_f32_e32 v168, v210, v168
	v_fmac_f32_e32 v168, v149, v144
	v_mov_b32_e32 v149, v168
	s_waitcnt lgkmcnt(0)
	v_mfma_f32_32x32x16_bf16 v[2:17], v[160:163], v[78:81], v[2:17]
	v_mfma_f32_32x32x16_bf16 v[18:33], v[164:167], v[78:81], v[18:33]
	v_mfma_f32_32x32x16_bf16 v[34:49], v[184:187], v[78:81], v[34:49]
	v_mfma_f32_32x32x16_bf16 v[50:65], v[188:191], v[78:81], v[50:65]
	s_branch .LBB0_227
